# P2: the 128 workgroups with 9 units (and idle tail) start ~17us late so their epilogue store bursts fall between the other half's (no added critical path)
# baseline (speedup 1.0000x reference)
;     __device__ __forceinline__ bool next(int i, Unit& u) const { if (!base.next(i >> 1, u)) return false; if (i & 1) { u.pm += 64; u.pn += 8; } return true; }
;     __device__ bool next(int i, Unit& u) const {
;         const long L = (long)i * G + c; if (L >= nwg) return false;
;         int wgid = (int)L; { const int q = nwg / NXCD, r = nwg % NXCD, xcd = wgid % NXCD, off = wgid / NXCD; wgid = (xcd < r ? xcd * (q + 1) : r * (q + 1) + (xcd - r) * q) + off; }
;         const int nig = WG * nN, gid = wgid / nig, fm = gid * WG, gsz = (nM - fm) < WG ? (nM - fm) : WG;
;         u.pm = fm + ((wgid % nig) % gsz); u.pn = (wgid % nig) / gsz; return true;
;     __device__ __forceinline__ bool next(int i, Unit& u) const { if (!base.next(i, u)) return false; const int p = u.pn;
;         u.pn = p < 16 ? 22 + p : p < 20 ? p - 16 : p < 24 ? p - 20 + 12 : p < 28 ? p - 24 + 4 : p < 32 ? p - 28 + 8 : p - 32 + 16; return true; }
.LBB0_188:
	s_or_b64 exec, exec, s[0:1]
	s_cmp_lt_u32 s55, 128
	s_cbranch_scc1 .Lp2skew_skip
	s_sleep 127
	s_sleep 127
	s_sleep 127
	s_sleep 127
	s_sleep 127
.Lp2skew_skip:
	s_waitcnt vmcnt(21)
	v_mov_b32_e32 v8, v186
	s_cmpk_lt_i32 s55, 0x980
	s_waitcnt lgkmcnt(0)
	s_barrier
	s_cselect_b64 s[4:5], -1, 0
	s_cmpk_gt_i32 s55, 0x97f
	v_readfirstlane_b32 s8, v8
	s_cbranch_scc1 .LBB0_193
	s_ashr_i32 s0, s55, 31
	s_lshr_b32 s0, s0, 29
	s_add_i32 s0, s55, s0
	s_ashr_i32 s1, s0, 3
	s_and_b32 s0, s0, -8
	s_sub_i32 s0, s55, s0
	s_cmp_lt_i32 s0, 0
	s_movk_i32 s2, 0x131
	s_cselect_b32 s2, s2, 0x130
	s_mul_i32 s0, s0, s2
	s_add_i32 s1, s0, s1
	s_mul_hi_i32 s0, s1, 0x6bca1af3
	s_lshr_b32 s2, s0, 31
	s_ashr_i32 s0, s0, 6
	s_add_i32 s0, s0, s2
	s_mul_i32 s2, s0, 0x98
	s_sub_i32 s1, s1, s2
	s_sext_i32_i16 s2, s1
	s_bfe_u32 s2, s2, 0x2001d
	s_add_i32 s2, s1, s2
	s_sext_i32_i16 s3, s2
	s_lshr_b32 s2, s3, 2
	s_ashr_i32 s3, s3, 2
	s_cmp_lt_i32 s1, 64
	s_mov_b32 s6, 22
	s_cbranch_scc1 .LBB0_192
	s_and_b32 s7, s3, 0xffff
	s_cmp_lt_u32 s7, 20
	s_mov_b32 s6, -16
	s_cbranch_scc1 .LBB0_192
	s_cmp_lt_u32 s7, 32
	s_cselect_b32 s6, 0xffffffec, -16
	s_cmp_gt_u32 s7, 23
	s_cselect_b32 s6, s6, -8
